# opt30b: as opt30 with the local-arrival poll every ~2048 cycles (s_sleep 32) so it does not contend with the arrival atomics; on v068
# baseline (speedup 1.0000x reference)
.Lmy_xs_23:
	v_mov_b32_e32 v0, 0x1000
	global_load_dword v0, v0, s[4:5] offset:1024 sc1
	s_waitcnt vmcnt(0)
	v_cmp_ge_u32_e32 vcc, v0, v2
	s_cbranch_vccnz .Lmy_xsd_23
	s_sleep 32
	s_branch .Lmy_xs_23

.Lmy_xs_1:
	v_mov_b32_e32 v0, 0x1000
	global_load_dword v0, v0, s[2:3] offset:1024 sc1
	s_waitcnt vmcnt(0)
	v_cmp_ge_u32_e32 vcc, v0, v2
	s_cbranch_vccnz .Lmy_xsd_1
	s_sleep 32
	s_branch .Lmy_xs_1
